# NA local tiles specialised per wave half: key subtiles entirely outside the 16-wide window (exactly-zero probabilities) skip K frags, QK MFMAs, bias reads, softmax and PV MFMAs; ds_read2 bias; permlan
# speedup vs baseline: 1.0160x; 1.0077x over previous
.LBB0_330:
	s_and_b64 vcc, exec, s[2:3]
	s_cbranch_vccz .LBB0_423
	v_readlane_b32 s2, v252, 62
	v_readlane_b32 s40, v254, 55
	v_readlane_b32 s46, v254, 61
	v_add_u32_e32 v0, s2, v125
	v_readlane_b32 s2, v252, 63
	v_readlane_b32 s47, v254, 62
	s_waitcnt vmcnt(0)
	v_add_u32_e32 v131, 0x9000, v222
	v_add_u32_e32 v115, s2, v0
	v_lshlrev_b32_e32 v0, 1, v0
	v_and_b32_e32 v127, 62, v0
	v_sub_u32_e64 v0, v127, 4 clamp
	v_bfe_u32 v2, v115, 5, 4
	v_min_u32_e32 v128, 56, v0
	v_lshlrev_b32_e32 v0, 7, v2
	v_lshlrev_b32_e32 v129, 6, v128
	v_lshlrev_b32_e32 v114, 6, v2
	v_lshl_add_u64 v[116:117], s[26:27], 0, v[0:1]
	v_mul_u32_u24_e32 v130, 0x1d1, v2
	v_lshl_add_u64 v[118:119], s[46:47], 0, v[0:1]
	v_sub_u32_e32 v132, v128, v127
	v_or_b32_e32 v133, 1, v128
	s_mov_b32 s34, 0
	v_readlane_b32 s41, v254, 56
	v_readlane_b32 s42, v254, 57
	v_readlane_b32 s43, v254, 58
	v_readlane_b32 s44, v254, 59
	v_readlane_b32 s45, v254, 60
	v_readlane_b32 s48, v254, 63
	v_readlane_b32 s49, v255, 0
	v_readlane_b32 s50, v255, 1
	v_readlane_b32 s51, v255, 2
	v_readlane_b32 s52, v255, 3
	v_readlane_b32 s53, v255, 4
	v_readlane_b32 s54, v255, 5
	v_readlane_b32 s55, v255, 6
	v_readfirstlane_b32 s100, v163
	s_branch .LBB0_333

.LBB0_342:
	v_add_u32_e32 v50, v58, v141
	v_mov_b64_e32 v[60:61], s[26:27]
	s_movk_i32 s10, 0x1800
	v_mad_i64_i32 v[50:51], s[2:3], v50, s10, v[60:61]
	v_lshl_add_u64 v[50:51], v[50:51], 0, v[0:1]
	v_lshlrev_b32_e32 v62, 1, v124
	v_mov_b32_e32 v63, v1
	v_add_u32_e32 v58, v58, v143
	v_lshl_add_u64 v[50:51], v[50:51], 0, v[62:63]
	v_mad_i64_i32 v[58:59], s[2:3], v58, s10, v[60:61]
	v_add_co_u32_e32 v54, vcc, 0x1000, v50
	v_lshl_add_u64 v[58:59], v[58:59], 0, v[0:1]
	s_nop 0
	v_addc_co_u32_e32 v55, vcc, 0, v51, vcc
	v_lshl_add_u64 v[58:59], v[58:59], 0, v[62:63]
	v_add_co_u32_e32 v62, vcc, 0x1000, v58
	global_load_dwordx4 v[50:53], v[50:51], off offset:2048
	s_nop 0
	global_load_dwordx4 v[54:57], v[54:55], off
	v_addc_co_u32_e32 v63, vcc, 0, v59, vcc
	global_load_dwordx4 v[58:61], v[58:59], off offset:2048
	s_nop 0
	global_load_dwordx4 v[62:65], v[62:63], off
	s_and_b32 s15, s14, 64
	v_add_u32_e32 v66, s24, v148
	s_cmp_gt_u32 s24, 8
	s_cselect_b64 s[10:11], -1, 0
	s_cmp_lt_u32 s24, 9
	v_cmp_gt_u32_e32 vcc, 8, v66
	s_movk_i32 s13, 0x1800
	s_cselect_b64 s[28:29], -1, 0
	s_or_b64 s[2:3], s[10:11], vcc
	s_and_saveexec_b64 s[38:39], s[2:3]
	s_cbranch_execz .LBB0_337
	v_or_b32_e32 v66, s15, v138
	v_mad_u32_u24 v82, v66, s16, v145
	s_cmp_lt_u32 s24, 9
	s_cbranch_scc0 .Lna_ctx_tile
	s_bitcmp1_b32 s100, 6
	s_cbranch_scc1 .Lna_loc_h1
	ds_read_b128 v[164:167], v82 offset:0
	ds_read_b128 v[168:171], v82 offset:64
	ds_read_b128 v[172:175], v82 offset:2304
	ds_read_b128 v[176:179], v82 offset:2368
	ds_read_b128 v[180:183], v82 offset:4608
	ds_read_b128 v[184:187], v82 offset:4672
	ds_read2_b32 v[224:225], v147 offset0:16 offset1:17
	ds_read2_b32 v[226:227], v147 offset0:18 offset1:19
	ds_read2_b32 v[228:229], v147 offset0:32 offset1:33
	ds_read2_b32 v[230:231], v147 offset0:34 offset1:35
	ds_read2_b32 v[232:233], v147 offset0:0 offset1:1
	ds_read2_b32 v[234:235], v147 offset0:2 offset1:3
	ds_read2_b32 v[236:237], v147 offset0:16 offset1:17
	ds_read2_b32 v[238:239], v147 offset0:18 offset1:19
	v_mov_b32_e32 v158, 0xf149f2ca
	s_waitcnt lgkmcnt(13)
	v_mfma_f32_16x16x32_bf16 v[90:93], v[164:167], v[38:41], 0
	v_mfma_f32_16x16x32_bf16 v[98:101], v[164:167], v[46:49], 0
	s_waitcnt lgkmcnt(12)
	v_mfma_f32_16x16x32_bf16 v[90:93], v[168:171], v[34:37], v[90:93]
	v_mfma_f32_16x16x32_bf16 v[98:101], v[168:171], v[42:45], v[98:101]
	ds_read2_b32 v[240:241], v147 offset0:32 offset1:33
	ds_read2_b32 v[242:243], v147 offset0:34 offset1:35
	s_waitcnt lgkmcnt(13)
	v_mfma_f32_16x16x32_bf16 v[94:97], v[172:175], v[38:41], 0
	v_mfma_f32_16x16x32_bf16 v[102:105], v[172:175], v[46:49], 0
	s_waitcnt lgkmcnt(12)
	v_mfma_f32_16x16x32_bf16 v[94:97], v[176:179], v[34:37], v[94:97]
	v_mfma_f32_16x16x32_bf16 v[102:105], v[176:179], v[42:45], v[102:105]
	s_waitcnt lgkmcnt(11)
	v_mfma_f32_16x16x32_bf16 v[106:109], v[180:183], v[46:49], 0
	s_waitcnt lgkmcnt(10)
	v_mfma_f32_16x16x32_bf16 v[106:109], v[184:187], v[42:45], v[106:109]
	s_waitcnt lgkmcnt(0)
	v_or_b32_e32 v160, s15, v135
	v_mul_u32_u24_e32 v160, 0x48, v160
	v_lshl_add_u32 v160, v160, 1, v136
	ds_read_b64_tr_b16 v[164:165], v160 offset:18432
	ds_read_b64_tr_b16 v[166:167], v160 offset:20736
	ds_read_b64_tr_b16 v[168:169], v160 offset:18464
	ds_read_b64_tr_b16 v[170:171], v160 offset:20768
	ds_read_b64_tr_b16 v[172:173], v160 offset:23040
	ds_read_b64_tr_b16 v[174:175], v160 offset:25344
	ds_read_b64_tr_b16 v[176:177], v160 offset:23072
	ds_read_b64_tr_b16 v[178:179], v160 offset:25376
	v_fmac_f32_e32 v224, 0x3e38aa3b, v90
	v_fmac_f32_e32 v225, 0x3e38aa3b, v91
	v_fmac_f32_e32 v226, 0x3e38aa3b, v92
	v_fmac_f32_e32 v227, 0x3e38aa3b, v93
	v_fmac_f32_e32 v228, 0x3e38aa3b, v94
	v_fmac_f32_e32 v229, 0x3e38aa3b, v95
	v_fmac_f32_e32 v230, 0x3e38aa3b, v96
	v_fmac_f32_e32 v231, 0x3e38aa3b, v97
	v_cndmask_b32_e64 v224, v158, v224, s[40:41]
	v_cndmask_b32_e64 v225, v158, v225, s[42:43]
	v_cndmask_b32_e64 v226, v158, v226, s[44:45]
	v_cndmask_b32_e64 v227, v158, v227, s[46:47]
	v_cndmask_b32_e64 v228, v158, v228, s[48:49]
	v_cndmask_b32_e64 v229, v158, v229, s[50:51]
	v_cndmask_b32_e64 v230, v158, v230, s[52:53]
	v_cndmask_b32_e64 v231, v158, v231, s[54:55]
	v_max3_f32 v150, v224, s18, v225
	v_max3_f32 v150, v150, v226, v227
	v_max3_f32 v150, v150, v228, v229
	v_max3_f32 v150, v150, v230, v231
	v_fmac_f32_e32 v232, 0x3e38aa3b, v98
	v_fmac_f32_e32 v233, 0x3e38aa3b, v99
	v_fmac_f32_e32 v234, 0x3e38aa3b, v100
	v_fmac_f32_e32 v235, 0x3e38aa3b, v101
	v_fmac_f32_e32 v236, 0x3e38aa3b, v102
	v_fmac_f32_e32 v237, 0x3e38aa3b, v103
	v_fmac_f32_e32 v238, 0x3e38aa3b, v104
	v_fmac_f32_e32 v239, 0x3e38aa3b, v105
	v_fmac_f32_e32 v240, 0x3e38aa3b, v106
	v_fmac_f32_e32 v241, 0x3e38aa3b, v107
	v_fmac_f32_e32 v242, 0x3e38aa3b, v108
	v_fmac_f32_e32 v243, 0x3e38aa3b, v109
	v_cndmask_b32_e64 v232, v158, v232, s[72:73]
	v_cndmask_b32_e64 v233, v158, v233, s[74:75]
	v_cndmask_b32_e64 v234, v158, v234, s[76:77]
	v_cndmask_b32_e64 v235, v158, v235, s[78:79]
	v_cndmask_b32_e64 v236, v158, v236, s[80:81]
	v_cndmask_b32_e64 v237, v158, v237, s[82:83]
	v_cndmask_b32_e64 v238, v158, v238, s[84:85]
	v_cndmask_b32_e64 v239, v158, v239, s[86:87]
	v_cndmask_b32_e64 v240, v158, v240, s[88:89]
	v_cndmask_b32_e64 v241, v158, v241, s[90:91]
	v_cndmask_b32_e64 v242, v158, v242, s[92:93]
	v_cndmask_b32_e64 v243, v158, v243, s[4:5]
	v_max3_f32 v151, v232, s18, v233
	v_max3_f32 v151, v151, v234, v235
	v_max3_f32 v151, v151, v236, v237
	v_max3_f32 v151, v151, v238, v239
	v_max3_f32 v151, v151, v240, v241
	v_max3_f32 v151, v151, v242, v243
	v_mov_b32_e32 v152, v150
	v_mov_b32_e32 v153, v151
	s_nop 0
	v_permlane16_swap_b32_e32 v152, v150
	v_permlane16_swap_b32_e32 v153, v151
	v_max_f32_e32 v150, v150, v152
	v_max_f32_e32 v151, v151, v153
	v_mov_b32_e32 v152, v150
	v_mov_b32_e32 v153, v151
	s_nop 0
	v_permlane32_swap_b32_e32 v152, v150
	v_permlane32_swap_b32_e32 v153, v151
	v_max_f32_e32 v150, v150, v152
	v_max_f32_e32 v151, v151, v153
	v_add_f32_e32 v110, 0x41000000, v144
	v_cmp_gt_f32_e32 vcc, v150, v110
	s_cbranch_vccz .Lna_l0_keep0
	v_max_f32_e32 v244, v144, v150
	v_sub_f32_e32 v110, v144, v244
	v_exp_f32_e32 v110, v110
	v_mov_b32_e32 v144, v244
	v_mul_f32_e32 v140, v140, v110
	v_pk_mul_f32 v[18:19], v[18:19], v[110:111] op_sel_hi:[1,0]
	v_pk_mul_f32 v[20:21], v[20:21], v[110:111] op_sel_hi:[1,0]
	v_pk_mul_f32 v[22:23], v[22:23], v[110:111] op_sel_hi:[1,0]
	v_pk_mul_f32 v[24:25], v[24:25], v[110:111] op_sel_hi:[1,0]
	v_pk_mul_f32 v[10:11], v[10:11], v[110:111] op_sel_hi:[1,0]
	v_pk_mul_f32 v[12:13], v[12:13], v[110:111] op_sel_hi:[1,0]
	v_pk_mul_f32 v[2:3], v[2:3], v[110:111] op_sel_hi:[1,0]
	v_pk_mul_f32 v[4:5], v[4:5], v[110:111] op_sel_hi:[1,0]
.Lna_l0_keep0:
	v_add_f32_e32 v112, 0x41000000, v142
	v_cmp_gt_f32_e32 vcc, v151, v112
	s_cbranch_vccz .Lna_l0_keep1
	v_max_f32_e32 v245, v142, v151
	v_sub_f32_e32 v112, v142, v245
	v_exp_f32_e32 v112, v112
	v_mov_b32_e32 v142, v245
	v_mul_f32_e32 v137, v137, v112
	v_pk_mul_f32 v[30:31], v[30:31], v[112:113] op_sel_hi:[1,0]
	v_pk_mul_f32 v[32:33], v[32:33], v[112:113] op_sel_hi:[1,0]
	v_pk_mul_f32 v[26:27], v[26:27], v[112:113] op_sel_hi:[1,0]
	v_pk_mul_f32 v[28:29], v[28:29], v[112:113] op_sel_hi:[1,0]
	v_pk_mul_f32 v[14:15], v[14:15], v[112:113] op_sel_hi:[1,0]
	v_pk_mul_f32 v[16:17], v[16:17], v[112:113] op_sel_hi:[1,0]
	v_pk_mul_f32 v[6:7], v[6:7], v[112:113] op_sel_hi:[1,0]
	v_pk_mul_f32 v[8:9], v[8:9], v[112:113] op_sel_hi:[1,0]
.Lna_l0_keep1:
	v_sub_f32_e32 v224, v224, v144
	v_sub_f32_e32 v225, v225, v144
	v_exp_f32_e32 v224, v224
	v_sub_f32_e32 v226, v226, v144
	v_exp_f32_e32 v225, v225
	v_sub_f32_e32 v227, v227, v144
	v_exp_f32_e32 v226, v226
	v_exp_f32_e32 v227, v227
	v_sub_f32_e32 v228, v228, v144
	v_sub_f32_e32 v229, v229, v144
	v_exp_f32_e32 v228, v228
	v_sub_f32_e32 v230, v230, v144
	v_exp_f32_e32 v229, v229
	v_sub_f32_e32 v231, v231, v144
	v_exp_f32_e32 v230, v230
	v_exp_f32_e32 v231, v231
	v_add_f32_e32 v246, 0, v224
	v_add_f32_e32 v246, v225, v246
	v_add_f32_e32 v246, v226, v246
	v_add_f32_e32 v246, v227, v246
	v_cvt_pk_bf16_f32 v66, v224, v225
	v_cvt_pk_bf16_f32 v67, v226, v227
	v_add_f32_e32 v246, v228, v246
	v_add_f32_e32 v246, v229, v246
	v_add_f32_e32 v246, v230, v246
	v_add_f32_e32 v246, v231, v246
	v_cvt_pk_bf16_f32 v68, v228, v229
	v_cvt_pk_bf16_f32 v69, v230, v231
	v_sub_f32_e32 v232, v232, v142
	v_sub_f32_e32 v233, v233, v142
	v_exp_f32_e32 v232, v232
	v_sub_f32_e32 v234, v234, v142
	v_exp_f32_e32 v233, v233
	v_sub_f32_e32 v235, v235, v142
	v_exp_f32_e32 v234, v234
	v_exp_f32_e32 v235, v235
	v_sub_f32_e32 v236, v236, v142
	v_sub_f32_e32 v237, v237, v142
	v_exp_f32_e32 v236, v236
	v_sub_f32_e32 v238, v238, v142
	v_exp_f32_e32 v237, v237
	v_sub_f32_e32 v239, v239, v142
	v_exp_f32_e32 v238, v238
	v_exp_f32_e32 v239, v239
	v_add_f32_e32 v247, 0, v232
	v_add_f32_e32 v247, v233, v247
	v_add_f32_e32 v247, v234, v247
	v_add_f32_e32 v247, v235, v247
	v_cvt_pk_bf16_f32 v74, v232, v233
	v_cvt_pk_bf16_f32 v75, v234, v235
	v_sub_f32_e32 v240, v240, v142
	v_sub_f32_e32 v241, v241, v142
	v_exp_f32_e32 v240, v240
	v_sub_f32_e32 v242, v242, v142
	v_exp_f32_e32 v241, v241
	v_sub_f32_e32 v243, v243, v142
	v_exp_f32_e32 v242, v242
	v_exp_f32_e32 v243, v243
	v_add_f32_e32 v247, v236, v247
	v_add_f32_e32 v247, v237, v247
	v_add_f32_e32 v247, v238, v247
	v_add_f32_e32 v247, v239, v247
	v_cvt_pk_bf16_f32 v76, v236, v237
	v_cvt_pk_bf16_f32 v77, v238, v239
	v_add_f32_e32 v140, v140, v246
	v_add_f32_e32 v247, v240, v247
	v_add_f32_e32 v247, v241, v247
	v_add_f32_e32 v247, v242, v247
	v_add_f32_e32 v247, v243, v247
	v_cvt_pk_bf16_f32 v78, v240, v241
	v_cvt_pk_bf16_f32 v79, v242, v243
	v_mov_b32_e32 v80, 0
	v_mov_b32_e32 v81, 0
	v_add_f32_e32 v137, v137, v247
	s_waitcnt lgkmcnt(6)
	ds_read_b64_tr_b16 v[180:181], v160 offset:18496
	ds_read_b64_tr_b16 v[182:183], v160 offset:20800
	ds_read_b64_tr_b16 v[184:185], v160 offset:18528
	ds_read_b64_tr_b16 v[186:187], v160 offset:20832
	ds_read_b64_tr_b16 v[154:155], v160 offset:23104
	ds_read_b64_tr_b16 v[156:157], v160 offset:25408
	ds_read_b64_tr_b16 v[200:201], v160 offset:23136
	ds_read_b64_tr_b16 v[202:203], v160 offset:25440
	v_mfma_f32_16x16x32_bf16 v[18:21], v[164:167], v[66:69], v[18:21]
	v_mfma_f32_16x16x32_bf16 v[30:33], v[164:167], v[74:77], v[30:33]
	s_waitcnt lgkmcnt(12)
	v_mfma_f32_16x16x32_bf16 v[22:25], v[168:171], v[66:69], v[22:25]
	v_mfma_f32_16x16x32_bf16 v[26:29], v[168:171], v[74:77], v[26:29]
	s_waitcnt lgkmcnt(10)
	v_mfma_f32_16x16x32_bf16 v[30:33], v[172:175], v[78:81], v[30:33]
	s_waitcnt lgkmcnt(8)
	v_mfma_f32_16x16x32_bf16 v[26:29], v[176:179], v[78:81], v[26:29]
	s_waitcnt lgkmcnt(6)
	v_mfma_f32_16x16x32_bf16 v[10:13], v[180:183], v[66:69], v[10:13]
	v_mfma_f32_16x16x32_bf16 v[14:17], v[180:183], v[74:77], v[14:17]
	s_waitcnt lgkmcnt(4)
	v_mfma_f32_16x16x32_bf16 v[2:5], v[184:187], v[66:69], v[2:5]
	v_mfma_f32_16x16x32_bf16 v[6:9], v[184:187], v[74:77], v[6:9]
	s_waitcnt lgkmcnt(2)
	v_mfma_f32_16x16x32_bf16 v[14:17], v[154:157], v[78:81], v[14:17]
	s_waitcnt lgkmcnt(0)
	v_mfma_f32_16x16x32_bf16 v[6:9], v[200:203], v[78:81], v[6:9]
	s_branch .LBB0_337
.Lna_loc_h1:
	ds_read_b128 v[164:167], v82 offset:2304
	ds_read_b128 v[168:171], v82 offset:2368
	ds_read_b128 v[172:175], v82 offset:4608
	ds_read_b128 v[176:179], v82 offset:4672
	ds_read_b128 v[180:183], v82 offset:6912
	ds_read_b128 v[184:187], v82 offset:6976
	ds_read2_b32 v[224:225], v147 offset0:32 offset1:33
	ds_read2_b32 v[226:227], v147 offset0:34 offset1:35
	ds_read2_b32 v[228:229], v147 offset0:48 offset1:49
	ds_read2_b32 v[230:231], v147 offset0:50 offset1:51
	ds_read2_b32 v[232:233], v147 offset0:64 offset1:65
	ds_read2_b32 v[234:235], v147 offset0:66 offset1:67
	ds_read2_b32 v[236:237], v147 offset0:32 offset1:33
	ds_read2_b32 v[238:239], v147 offset0:34 offset1:35
	v_mov_b32_e32 v158, 0xf149f2ca
	s_waitcnt lgkmcnt(13)
	v_mfma_f32_16x16x32_bf16 v[90:93], v[164:167], v[38:41], 0
	s_waitcnt lgkmcnt(12)
	v_mfma_f32_16x16x32_bf16 v[90:93], v[168:171], v[34:37], v[90:93]
	ds_read2_b32 v[240:241], v147 offset0:48 offset1:49
	ds_read2_b32 v[242:243], v147 offset0:50 offset1:51
	s_waitcnt lgkmcnt(13)
	v_mfma_f32_16x16x32_bf16 v[94:97], v[172:175], v[38:41], 0
	v_mfma_f32_16x16x32_bf16 v[102:105], v[172:175], v[46:49], 0
	s_waitcnt lgkmcnt(12)
	v_mfma_f32_16x16x32_bf16 v[94:97], v[176:179], v[34:37], v[94:97]
	v_mfma_f32_16x16x32_bf16 v[102:105], v[176:179], v[42:45], v[102:105]
	s_waitcnt lgkmcnt(11)
	v_mfma_f32_16x16x32_bf16 v[98:101], v[180:183], v[38:41], 0
	v_mfma_f32_16x16x32_bf16 v[106:109], v[180:183], v[46:49], 0
	s_waitcnt lgkmcnt(10)
	v_mfma_f32_16x16x32_bf16 v[98:101], v[184:187], v[34:37], v[98:101]
	v_mfma_f32_16x16x32_bf16 v[106:109], v[184:187], v[42:45], v[106:109]
	s_waitcnt lgkmcnt(0)
	v_or_b32_e32 v160, s15, v135
	v_mul_u32_u24_e32 v160, 0x48, v160
	v_lshl_add_u32 v160, v160, 1, v136
	ds_read_b64_tr_b16 v[164:165], v160 offset:18432
	ds_read_b64_tr_b16 v[166:167], v160 offset:20736
	ds_read_b64_tr_b16 v[168:169], v160 offset:18464
	ds_read_b64_tr_b16 v[170:171], v160 offset:20768
	ds_read_b64_tr_b16 v[172:173], v160 offset:23040
	ds_read_b64_tr_b16 v[174:175], v160 offset:25344
	ds_read_b64_tr_b16 v[176:177], v160 offset:23072
	ds_read_b64_tr_b16 v[178:179], v160 offset:25376
	v_fmac_f32_e32 v224, 0x3e38aa3b, v90
	v_fmac_f32_e32 v225, 0x3e38aa3b, v91
	v_fmac_f32_e32 v226, 0x3e38aa3b, v92
	v_fmac_f32_e32 v227, 0x3e38aa3b, v93
	v_fmac_f32_e32 v228, 0x3e38aa3b, v94
	v_fmac_f32_e32 v229, 0x3e38aa3b, v95
	v_fmac_f32_e32 v230, 0x3e38aa3b, v96
	v_fmac_f32_e32 v231, 0x3e38aa3b, v97
	v_fmac_f32_e32 v232, 0x3e38aa3b, v98
	v_fmac_f32_e32 v233, 0x3e38aa3b, v99
	v_fmac_f32_e32 v234, 0x3e38aa3b, v100
	v_fmac_f32_e32 v235, 0x3e38aa3b, v101
	v_cndmask_b32_e64 v224, v158, v224, s[48:49]
	v_cndmask_b32_e64 v225, v158, v225, s[50:51]
	v_cndmask_b32_e64 v226, v158, v226, s[52:53]
	v_cndmask_b32_e64 v227, v158, v227, s[54:55]
	v_cndmask_b32_e64 v228, v158, v228, s[56:57]
	v_cndmask_b32_e64 v229, v158, v229, s[58:59]
	v_cndmask_b32_e64 v230, v158, v230, s[60:61]
	v_cndmask_b32_e64 v231, v158, v231, s[62:63]
	v_cndmask_b32_e64 v232, v158, v232, s[64:65]
	v_cndmask_b32_e64 v233, v158, v233, s[66:67]
	v_cndmask_b32_e64 v234, v158, v234, s[68:69]
	v_cndmask_b32_e64 v235, v158, v235, s[70:71]
	v_max3_f32 v150, v224, s18, v225
	v_max3_f32 v150, v150, v226, v227
	v_max3_f32 v150, v150, v228, v229
	v_max3_f32 v150, v150, v230, v231
	v_max3_f32 v150, v150, v232, v233
	v_max3_f32 v150, v150, v234, v235
	v_fmac_f32_e32 v236, 0x3e38aa3b, v102
	v_fmac_f32_e32 v237, 0x3e38aa3b, v103
	v_fmac_f32_e32 v238, 0x3e38aa3b, v104
	v_fmac_f32_e32 v239, 0x3e38aa3b, v105
	v_fmac_f32_e32 v240, 0x3e38aa3b, v106
	v_fmac_f32_e32 v241, 0x3e38aa3b, v107
	v_fmac_f32_e32 v242, 0x3e38aa3b, v108
	v_fmac_f32_e32 v243, 0x3e38aa3b, v109
	v_cndmask_b32_e64 v236, v158, v236, s[88:89]
	v_cndmask_b32_e64 v237, v158, v237, s[90:91]
	v_cndmask_b32_e64 v238, v158, v238, s[92:93]
	v_cndmask_b32_e64 v239, v158, v239, s[4:5]
	v_cndmask_b32_e64 v240, v158, v240, s[94:95]
	v_cndmask_b32_e64 v241, v158, v241, s[6:7]
	v_cndmask_b32_e64 v242, v158, v242, s[8:9]
	v_cndmask_b32_e64 v243, v158, v243, s[96:97]
	v_max3_f32 v151, v236, s18, v237
	v_max3_f32 v151, v151, v238, v239
	v_max3_f32 v151, v151, v240, v241
	v_max3_f32 v151, v151, v242, v243
	v_mov_b32_e32 v152, v150
	v_mov_b32_e32 v153, v151
	s_nop 0
	v_permlane16_swap_b32_e32 v152, v150
	v_permlane16_swap_b32_e32 v153, v151
	v_max_f32_e32 v150, v150, v152
	v_max_f32_e32 v151, v151, v153
	v_mov_b32_e32 v152, v150
	v_mov_b32_e32 v153, v151
	s_nop 0
	v_permlane32_swap_b32_e32 v152, v150
	v_permlane32_swap_b32_e32 v153, v151
	v_max_f32_e32 v150, v150, v152
	v_max_f32_e32 v151, v151, v153
	v_add_f32_e32 v110, 0x41000000, v144
	v_cmp_gt_f32_e32 vcc, v150, v110
	s_cbranch_vccz .Lna_l1_keep0
	v_max_f32_e32 v244, v144, v150
	v_sub_f32_e32 v110, v144, v244
	v_exp_f32_e32 v110, v110
	v_mov_b32_e32 v144, v244
	v_mul_f32_e32 v140, v140, v110
	v_pk_mul_f32 v[18:19], v[18:19], v[110:111] op_sel_hi:[1,0]
	v_pk_mul_f32 v[20:21], v[20:21], v[110:111] op_sel_hi:[1,0]
	v_pk_mul_f32 v[22:23], v[22:23], v[110:111] op_sel_hi:[1,0]
	v_pk_mul_f32 v[24:25], v[24:25], v[110:111] op_sel_hi:[1,0]
	v_pk_mul_f32 v[10:11], v[10:11], v[110:111] op_sel_hi:[1,0]
	v_pk_mul_f32 v[12:13], v[12:13], v[110:111] op_sel_hi:[1,0]
	v_pk_mul_f32 v[2:3], v[2:3], v[110:111] op_sel_hi:[1,0]
	v_pk_mul_f32 v[4:5], v[4:5], v[110:111] op_sel_hi:[1,0]

.Lna_l1_keep1:
	v_sub_f32_e32 v224, v224, v144
	v_sub_f32_e32 v225, v225, v144
	v_exp_f32_e32 v224, v224
	v_sub_f32_e32 v226, v226, v144
	v_exp_f32_e32 v225, v225
	v_sub_f32_e32 v227, v227, v144
	v_exp_f32_e32 v226, v226
	v_exp_f32_e32 v227, v227
	v_mov_b32_e32 v66, 0
	v_mov_b32_e32 v67, 0
	v_sub_f32_e32 v228, v228, v144
	v_sub_f32_e32 v229, v229, v144
	v_exp_f32_e32 v228, v228
	v_sub_f32_e32 v230, v230, v144
	v_exp_f32_e32 v229, v229
	v_sub_f32_e32 v231, v231, v144
	v_exp_f32_e32 v230, v230
	v_exp_f32_e32 v231, v231
	v_add_f32_e32 v246, 0, v224
	v_add_f32_e32 v246, v225, v246
	v_add_f32_e32 v246, v226, v246
	v_add_f32_e32 v246, v227, v246
	v_cvt_pk_bf16_f32 v68, v224, v225
	v_cvt_pk_bf16_f32 v69, v226, v227
	v_sub_f32_e32 v232, v232, v144
	v_sub_f32_e32 v233, v233, v144
	v_exp_f32_e32 v232, v232
	v_sub_f32_e32 v234, v234, v144
	v_exp_f32_e32 v233, v233
	v_sub_f32_e32 v235, v235, v144
	v_exp_f32_e32 v234, v234
	v_exp_f32_e32 v235, v235
	v_add_f32_e32 v246, v228, v246
	v_add_f32_e32 v246, v229, v246
	v_add_f32_e32 v246, v230, v246
	v_add_f32_e32 v246, v231, v246
	v_cvt_pk_bf16_f32 v70, v228, v229
	v_cvt_pk_bf16_f32 v71, v230, v231
	v_add_f32_e32 v246, v232, v246
	v_add_f32_e32 v246, v233, v246
	v_add_f32_e32 v246, v234, v246
	v_add_f32_e32 v246, v235, v246
	v_cvt_pk_bf16_f32 v72, v232, v233
	v_cvt_pk_bf16_f32 v73, v234, v235
	v_sub_f32_e32 v236, v236, v142
	v_sub_f32_e32 v237, v237, v142
	v_exp_f32_e32 v236, v236
	v_sub_f32_e32 v238, v238, v142
	v_exp_f32_e32 v237, v237
	v_sub_f32_e32 v239, v239, v142
	v_exp_f32_e32 v238, v238
	v_exp_f32_e32 v239, v239
	v_sub_f32_e32 v240, v240, v142
	v_sub_f32_e32 v241, v241, v142
	v_exp_f32_e32 v240, v240
	v_sub_f32_e32 v242, v242, v142
	v_exp_f32_e32 v241, v241
	v_sub_f32_e32 v243, v243, v142
	v_exp_f32_e32 v242, v242
	v_exp_f32_e32 v243, v243
	v_add_f32_e32 v247, 0, v236
	v_add_f32_e32 v247, v237, v247
	v_add_f32_e32 v247, v238, v247
	v_add_f32_e32 v247, v239, v247
	v_cvt_pk_bf16_f32 v78, v236, v237
	v_cvt_pk_bf16_f32 v79, v238, v239
	v_add_f32_e32 v140, v140, v246
	v_add_f32_e32 v247, v240, v247
	v_add_f32_e32 v247, v241, v247
	v_add_f32_e32 v247, v242, v247
	v_add_f32_e32 v247, v243, v247
	v_cvt_pk_bf16_f32 v80, v240, v241
	v_cvt_pk_bf16_f32 v81, v242, v243
	v_add_f32_e32 v137, v137, v247
	s_waitcnt lgkmcnt(6)
	ds_read_b64_tr_b16 v[180:181], v160 offset:18496
	ds_read_b64_tr_b16 v[182:183], v160 offset:20800
	ds_read_b64_tr_b16 v[184:185], v160 offset:18528
	ds_read_b64_tr_b16 v[186:187], v160 offset:20832
	ds_read_b64_tr_b16 v[154:155], v160 offset:23104
	ds_read_b64_tr_b16 v[156:157], v160 offset:25408
	ds_read_b64_tr_b16 v[200:201], v160 offset:23136
	ds_read_b64_tr_b16 v[202:203], v160 offset:25440
	v_mfma_f32_16x16x32_bf16 v[18:21], v[164:167], v[66:69], v[18:21]
	s_waitcnt lgkmcnt(12)
	v_mfma_f32_16x16x32_bf16 v[22:25], v[168:171], v[66:69], v[22:25]
	s_waitcnt lgkmcnt(10)
	v_mfma_f32_16x16x32_bf16 v[18:21], v[172:175], v[70:73], v[18:21]
	v_mfma_f32_16x16x32_bf16 v[30:33], v[172:175], v[78:81], v[30:33]
	s_waitcnt lgkmcnt(8)
	v_mfma_f32_16x16x32_bf16 v[22:25], v[176:179], v[70:73], v[22:25]
	v_mfma_f32_16x16x32_bf16 v[26:29], v[176:179], v[78:81], v[26:29]
	s_waitcnt lgkmcnt(6)
	v_mfma_f32_16x16x32_bf16 v[10:13], v[180:183], v[66:69], v[10:13]
	s_waitcnt lgkmcnt(4)
	v_mfma_f32_16x16x32_bf16 v[2:5], v[184:187], v[66:69], v[2:5]
	s_waitcnt lgkmcnt(2)
	v_mfma_f32_16x16x32_bf16 v[10:13], v[154:157], v[70:73], v[10:13]
	v_mfma_f32_16x16x32_bf16 v[14:17], v[154:157], v[78:81], v[14:17]
	s_waitcnt lgkmcnt(0)
	v_mfma_f32_16x16x32_bf16 v[2:5], v[200:203], v[70:73], v[2:5]
	v_mfma_f32_16x16x32_bf16 v[6:9], v[200:203], v[78:81], v[6:9]
	s_branch .LBB0_337
.Lna_ctx_tile:
	ds_read_b128 v[66:69], v82
	ds_read_b128 v[70:73], v82 offset:64
	ds_read_b128 v[74:77], v82 offset:2304
	ds_read_b128 v[78:81], v82 offset:2368
	ds_read_b128 v[90:93], v82 offset:4608
	ds_read_b128 v[94:97], v82 offset:4672
	ds_read_b128 v[110:113], v82 offset:6912
	ds_read_b128 v[150:153], v82 offset:6976
	s_waitcnt lgkmcnt(7)
	v_mfma_f32_16x16x32_bf16 v[82:85], v[66:69], v[38:41], 0
	v_mfma_f32_16x16x32_bf16 v[66:69], v[66:69], v[46:49], 0
	s_waitcnt lgkmcnt(6)
	v_mfma_f32_16x16x32_bf16 v[98:101], v[70:73], v[34:37], v[82:85]
	v_mfma_f32_16x16x32_bf16 v[82:85], v[70:73], v[42:45], v[66:69]
	s_waitcnt lgkmcnt(5)
	v_mfma_f32_16x16x32_bf16 v[66:69], v[74:77], v[38:41], 0
	v_mfma_f32_16x16x32_bf16 v[70:73], v[74:77], v[46:49], 0
	s_waitcnt lgkmcnt(4)
	v_mfma_f32_16x16x32_bf16 v[102:105], v[78:81], v[34:37], v[66:69]
	v_mfma_f32_16x16x32_bf16 v[86:89], v[78:81], v[42:45], v[70:73]
	s_waitcnt lgkmcnt(3)
	v_mfma_f32_16x16x32_bf16 v[66:69], v[90:93], v[38:41], 0
	v_mfma_f32_16x16x32_bf16 v[70:73], v[90:93], v[46:49], 0
	s_waitcnt lgkmcnt(2)
	v_mfma_f32_16x16x32_bf16 v[106:109], v[94:97], v[34:37], v[66:69]
	v_mfma_f32_16x16x32_bf16 v[90:93], v[94:97], v[42:45], v[70:73]
	s_waitcnt lgkmcnt(1)
	v_mfma_f32_16x16x32_bf16 v[66:69], v[110:113], v[38:41], 0
	v_mfma_f32_16x16x32_bf16 v[70:73], v[110:113], v[46:49], 0
	s_waitcnt lgkmcnt(0)
	v_mfma_f32_16x16x32_bf16 v[110:113], v[150:153], v[34:37], v[66:69]
	v_mfma_f32_16x16x32_bf16 v[94:97], v[150:153], v[42:45], v[70:73]
	s_mov_b64 s[30:31], -1
	s_and_b64 vcc, exec, s[28:29]
	s_cbranch_vccz .LBB0_377
	s_nop 0
	v_mov_b32_e32 v160, 0xf149f2ca
	ds_read_b32 v66, v147 offset:64
	ds_read_b32 v67, v147 offset:68
	ds_read_b32 v68, v147 offset:72
	ds_read_b32 v69, v147 offset:76
	ds_read_b32 v70, v147 offset:128
	ds_read_b32 v71, v147 offset:132
	ds_read_b32 v72, v147 offset:136
	ds_read_b32 v73, v147 offset:140
	ds_read_b32 v74, v147 offset:192
	ds_read_b32 v75, v147 offset:196
	ds_read_b32 v76, v147 offset:200
	ds_read_b32 v77, v147 offset:204
	ds_read_b32 v78, v147 offset:256
	ds_read_b32 v79, v147 offset:260
	ds_read_b32 v80, v147 offset:264
	ds_read_b32 v81, v147 offset:268
	s_waitcnt lgkmcnt(0)
	v_fmac_f32_e32 v66, 0x3e38aa3b, v98
	v_fmac_f32_e32 v67, 0x3e38aa3b, v99
	v_fmac_f32_e32 v68, 0x3e38aa3b, v100
	v_fmac_f32_e32 v69, 0x3e38aa3b, v101
	v_fmac_f32_e32 v70, 0x3e38aa3b, v102
	v_fmac_f32_e32 v71, 0x3e38aa3b, v103
	v_fmac_f32_e32 v72, 0x3e38aa3b, v104
	v_fmac_f32_e32 v73, 0x3e38aa3b, v105
	v_fmac_f32_e32 v74, 0x3e38aa3b, v106
	v_fmac_f32_e32 v75, 0x3e38aa3b, v107
	v_fmac_f32_e32 v76, 0x3e38aa3b, v108
	v_fmac_f32_e32 v77, 0x3e38aa3b, v109
	v_fmac_f32_e32 v78, 0x3e38aa3b, v110
	v_fmac_f32_e32 v79, 0x3e38aa3b, v111
	v_fmac_f32_e32 v80, 0x3e38aa3b, v112
	v_fmac_f32_e32 v81, 0x3e38aa3b, v113
	v_cndmask_b32_e64 v66, v160, v66, s[40:41]
	v_cndmask_b32_e64 v67, v160, v67, s[42:43]
	v_cndmask_b32_e64 v68, v160, v68, s[44:45]
	v_cndmask_b32_e64 v69, v160, v69, s[46:47]
	v_cndmask_b32_e64 v70, v160, v70, s[48:49]
	v_cndmask_b32_e64 v71, v160, v71, s[50:51]
	v_cndmask_b32_e64 v72, v160, v72, s[52:53]
	v_cndmask_b32_e64 v73, v160, v73, s[54:55]
	v_cndmask_b32_e64 v74, v160, v74, s[56:57]
	v_cndmask_b32_e64 v75, v160, v75, s[58:59]
	v_cndmask_b32_e64 v76, v160, v76, s[60:61]
	v_cndmask_b32_e64 v77, v160, v77, s[62:63]
	v_cndmask_b32_e64 v78, v160, v78, s[64:65]
	v_cndmask_b32_e64 v79, v160, v79, s[66:67]
	v_cndmask_b32_e64 v80, v160, v80, s[68:69]
	v_cndmask_b32_e64 v81, v160, v81, s[70:71]
	v_max3_f32 v150, v66, s18, v67
	v_max3_f32 v150, v150, v68, v69
	v_max3_f32 v150, v150, v70, v71
	v_max3_f32 v150, v150, v72, v73
	v_max3_f32 v150, v150, v74, v75
	v_max3_f32 v150, v150, v76, v77
	v_max3_f32 v150, v150, v78, v79
	v_max3_f32 v152, v150, v80, v81
	s_mov_b64 s[30:31], 0
